# Hoist the serialized per-row epilogue loads (rstd / partial sums) of the two MLP-up GEMM phases to the epilogue top into dead fragment registers; removes 7 store-drain round trips per tile
# baseline (speedup 1.0000x reference)
; __device__ __forceinline__ unsigned cvt_pk_bf16(float lo, float hi) { unsigned r; asm volatile("v_cvt_pk_bf16_f32 %0, %1, %2" : "=v"(r) : "v"(lo), "v"(hi)); return r; }
;     __device__ __forceinline__ void operator()(const f32x4 (&acc)[2][2][4][2], const Unit& u, int wr, int wc, int fr, int fq) const {
;         const int row0 = u.pm * BM + wr * 64 + fr, col0 = u.pn * BM + wc * 32 + 8 * fq;
;         const int mr = u.pm < (ML / BM) ? u.pm / (SEQ / BM) : BATCH;
;         f32x4 bv[2][2];
; #pragma unroll
;         for (int bj = 0; bj < 2; ++bj)
; #pragma unroll
;             for (int n = 0; n < 2; ++n) bv[bj][n] = *(const f32x4*)(shw + (size_t)mr * FF + col0 + bj * HALF + 4 * n);
; #pragma unroll
;         for (int ai = 0; ai < 2; ++ai)
; #pragma unroll
;             for (int m = 0; m < 4; ++m) { const int row = row0 + ai * HALF + m * 16; bf16_t* rowp = O + (size_t)row * FF + col0; float rs;
;                 if constexpr (SUMP) { const f32x4 p0 = *(const f32x4*)(rstd + (size_t)row * 32 + 8 * fq), p1 = *(const f32x4*)(rstd + (size_t)row * 32 + 8 * fq + 4);
;                     float t = ((p0[0] + p0[1]) + (p0[2] + p0[3])) + ((p1[0] + p1[1]) + (p1[2] + p1[3])); t += __shfl_xor(t, 16); t += __shfl_xor(t, 32); rs = rsqrtf(t * (1.f / D) + EPS); }
;                 else rs = rstd[row];
; #pragma unroll
;                 for (int bj = 0; bj < 2; ++bj) { f32x4 v0 = acc[ai][bj][m][0] * rs + bv[bj][0], v1 = acc[ai][bj][m][1] * rs + bv[bj][1];
; #pragma unroll
;                     for (int e = 0; e < 4; ++e) { const float a = fmaxf(v0[e], 0.f), b = fmaxf(v1[e], 0.f); v0[e] = a * a; v1[e] = b * b; }
;                     u32x4 w; w.x = cvt_pk_bf16(v0[0], v0[1]); w.y = cvt_pk_bf16(v0[2], v0[3]); w.z = cvt_pk_bf16(v1[0], v1[1]); w.w = cvt_pk_bf16(v1[2], v1[3]);
;                     *(u32x4*)(rowp + bj * HALF) = w; } }
.LBB0_550:
	s_lshl_b64 s[52:53], s[68:69], 2
	v_lshl_or_b32 v166, s83, 8, v173
	v_lshl_add_u32 v168, s54, 8, v145
	s_add_u32 s52, s94, s52
	s_addc_u32 s53, s95, s53
	v_ashrrev_i32_e32 v167, 31, v166
	v_ashrrev_i32_e32 v169, 31, v168
	v_lshl_add_u64 v[112:113], v[166:167], 2, s[52:53]
	v_lshl_add_u64 v[164:165], v[168:169], 2, s[6:7]
	global_load_dword v178, v[164:165], off
	global_load_dword v190, v[164:165], off offset:64
	global_load_dword v191, v[164:165], off offset:128
	global_load_dword v192, v[164:165], off offset:192
	global_load_dword v193, v[164:165], off offset:512
	global_load_dword v194, v[164:165], off offset:576
	global_load_dword v195, v[164:165], off offset:640
	global_load_dword v196, v[164:165], off offset:704
	global_load_dwordx4 v[124:127], v[112:113], off
	global_load_dwordx4 v[120:123], v[112:113], off offset:16
	global_load_dwordx4 v[116:119], v[112:113], off offset:512
	s_nop 0
	global_load_dwordx4 v[112:115], v[112:113], off offset:528
	v_lshlrev_b64 v[182:183], 14, v[168:169]
	v_or_b32_e32 v180, 16, v168
	v_lshlrev_b64 v[170:171], 1, v[166:167]
	v_lshl_add_u64 v[166:167], s[16:17], 0, v[182:183]
	v_ashrrev_i32_e32 v181, 31, v180
	v_lshl_add_u64 v[166:167], v[166:167], 0, v[170:171]
	v_lshl_add_u64 v[182:183], v[180:181], 2, s[6:7]
	s_mov_b32 s37, 0x200000
	s_mov_b64 s[52:53], 0x200000
	s_waitcnt vmcnt(0)
	v_pk_fma_f32 v[142:143], v[142:143], v[178:179], v[126:127] op_sel_hi:[1,0,1]
	v_pk_fma_f32 v[140:141], v[140:141], v[178:179], v[124:125] op_sel_hi:[1,0,1]
	v_pk_fma_f32 v[138:139], v[138:139], v[178:179], v[122:123] op_sel_hi:[1,0,1]
	v_pk_fma_f32 v[136:137], v[136:137], v[178:179], v[120:121] op_sel_hi:[1,0,1]
	v_pk_fma_f32 v[130:131], v[130:131], v[178:179], v[114:115] op_sel_hi:[1,0,1]
	v_pk_fma_f32 v[128:129], v[128:129], v[178:179], v[112:113] op_sel_hi:[1,0,1]
	v_pk_fma_f32 v[134:135], v[134:135], v[178:179], v[118:119] op_sel_hi:[1,0,1]
	v_pk_fma_f32 v[132:133], v[132:133], v[178:179], v[116:117] op_sel_hi:[1,0,1]
	v_max_f32_e32 v140, 0, v140
	v_max_f32_e32 v136, 0, v136
	v_max_f32_e32 v141, 0, v141
	v_max_f32_e32 v137, 0, v137
	v_max_f32_e32 v142, 0, v142
	v_max_f32_e32 v138, 0, v138
	v_max_f32_e32 v143, 0, v143
	v_max_f32_e32 v139, 0, v139
	v_max_f32_e32 v128, 0, v128
	v_max_f32_e32 v129, 0, v129
	v_max_f32_e32 v130, 0, v130
	v_max_f32_e32 v131, 0, v131
	v_max_f32_e32 v132, 0, v132
	v_max_f32_e32 v133, 0, v133
	v_max_f32_e32 v134, 0, v134
	v_max_f32_e32 v135, 0, v135
	v_mul_f32_e32 v140, v140, v140
	v_mul_f32_e32 v136, v136, v136
	v_mul_f32_e32 v141, v141, v141
	v_mul_f32_e32 v137, v137, v137
	v_mul_f32_e32 v142, v142, v142
	v_mul_f32_e32 v138, v138, v138
	v_mul_f32_e32 v143, v143, v143
	v_mul_f32_e32 v139, v139, v139
	v_mul_f32_e32 v169, v128, v128
	v_mul_f32_e32 v177, v129, v129
	v_mul_f32_e32 v178, v130, v130
	v_mul_f32_e32 v179, v131, v131
	v_cvt_pk_bf16_f32 v128, v140, v141
	v_cvt_pk_bf16_f32 v129, v142, v143
	v_cvt_pk_bf16_f32 v130, v136, v137
	v_cvt_pk_bf16_f32 v131, v138, v139
	v_mul_f32_e32 v132, v132, v132
	v_mul_f32_e32 v133, v133, v133
	v_mul_f32_e32 v134, v134, v134
	v_mul_f32_e32 v135, v135, v135
	global_store_dwordx4 v[166:167], v[128:131], off
	s_nop 1
	v_cvt_pk_bf16_f32 v128, v132, v133
	v_cvt_pk_bf16_f32 v129, v134, v135
	v_cvt_pk_bf16_f32 v130, v169, v177
	v_cvt_pk_bf16_f32 v131, v178, v179
	global_store_dwordx4 v[166:167], v[128:131], off offset:256
	s_nop 1
	v_mov_b32_e32 v128, v190
	v_lshlrev_b64 v[132:133], 14, v[180:181]
	v_or_b32_e32 v130, 32, v168
	v_lshl_add_u64 v[132:133], s[16:17], 0, v[132:133]
	v_ashrrev_i32_e32 v131, 31, v130
	v_lshl_add_u64 v[132:133], v[132:133], 0, v[170:171]
	v_lshl_add_u64 v[134:135], v[130:131], 2, s[6:7]
	v_pk_fma_f32 v[110:111], v[110:111], v[128:129], v[126:127] op_sel_hi:[1,0,1]
	v_pk_fma_f32 v[108:109], v[108:109], v[128:129], v[124:125] op_sel_hi:[1,0,1]
	v_pk_fma_f32 v[106:107], v[106:107], v[128:129], v[122:123] op_sel_hi:[1,0,1]
	v_pk_fma_f32 v[104:105], v[104:105], v[128:129], v[120:121] op_sel_hi:[1,0,1]
	v_pk_fma_f32 v[98:99], v[98:99], v[128:129], v[114:115] op_sel_hi:[1,0,1]
	v_pk_fma_f32 v[96:97], v[96:97], v[128:129], v[112:113] op_sel_hi:[1,0,1]
	v_pk_fma_f32 v[102:103], v[102:103], v[128:129], v[118:119] op_sel_hi:[1,0,1]
	v_pk_fma_f32 v[100:101], v[100:101], v[128:129], v[116:117] op_sel_hi:[1,0,1]
	v_max_f32_e32 v108, 0, v108
	v_max_f32_e32 v104, 0, v104
	v_max_f32_e32 v109, 0, v109
	v_max_f32_e32 v105, 0, v105
	v_max_f32_e32 v110, 0, v110
	v_max_f32_e32 v106, 0, v106
	v_max_f32_e32 v111, 0, v111
	v_max_f32_e32 v107, 0, v107
	v_max_f32_e32 v96, 0, v96
	v_max_f32_e32 v97, 0, v97
	v_max_f32_e32 v98, 0, v98
	v_max_f32_e32 v99, 0, v99
	v_max_f32_e32 v100, 0, v100
	v_max_f32_e32 v101, 0, v101
	v_max_f32_e32 v102, 0, v102
	v_max_f32_e32 v103, 0, v103
	v_mul_f32_e32 v108, v108, v108
	v_mul_f32_e32 v104, v104, v104
	v_mul_f32_e32 v109, v109, v109
	v_mul_f32_e32 v105, v105, v105
	v_mul_f32_e32 v110, v110, v110
	v_mul_f32_e32 v106, v106, v106
	v_mul_f32_e32 v111, v111, v111
	v_mul_f32_e32 v107, v107, v107
	v_mul_f32_e32 v128, v96, v96
	v_mul_f32_e32 v129, v97, v97
	v_mul_f32_e32 v136, v98, v98
	v_mul_f32_e32 v137, v99, v99
	v_cvt_pk_bf16_f32 v96, v108, v109
	v_cvt_pk_bf16_f32 v97, v110, v111
	v_cvt_pk_bf16_f32 v98, v104, v105
	v_cvt_pk_bf16_f32 v99, v106, v107
	v_mul_f32_e32 v100, v100, v100
	v_mul_f32_e32 v101, v101, v101
	v_mul_f32_e32 v102, v102, v102
	v_mul_f32_e32 v103, v103, v103
	global_store_dwordx4 v[132:133], v[96:99], off
	s_nop 1
	v_cvt_pk_bf16_f32 v96, v100, v101
	v_cvt_pk_bf16_f32 v97, v102, v103
	v_cvt_pk_bf16_f32 v98, v128, v129
	v_cvt_pk_bf16_f32 v99, v136, v137
	global_store_dwordx4 v[132:133], v[96:99], off offset:256
; __device__ __forceinline__ unsigned cvt_pk_bf16(float lo, float hi) { unsigned r; asm volatile("v_cvt_pk_bf16_f32 %0, %1, %2" : "=v"(r) : "v"(lo), "v"(hi)); return r; }
;     __device__ __forceinline__ void operator()(const f32x4 (&acc)[2][2][4][2], const Unit& u, int wr, int wc, int fr, int fq) const {
;     ...
;             for (int m = 0; m < 4; ++m) { const int row = row0 + ai * HALF + m * 16; bf16_t* rowp = O + (size_t)row * FF + col0; float rs;
;                 if constexpr (SUMP) { const f32x4 p0 = *(const f32x4*)(rstd + (size_t)row * 32 + 8 * fq), p1 = *(const f32x4*)(rstd + (size_t)row * 32 + 8 * fq + 4);
;                     float t = ((p0[0] + p0[1]) + (p0[2] + p0[3])) + ((p1[0] + p1[1]) + (p1[2] + p1[3])); t += __shfl_xor(t, 16); t += __shfl_xor(t, 32); rs = rsqrtf(t * (1.f / D) + EPS); }
;                 else rs = rstd[row];
; #pragma unroll
;                 for (int bj = 0; bj < 2; ++bj) { f32x4 v0 = acc[ai][bj][m][0] * rs + bv[bj][0], v1 = acc[ai][bj][m][1] * rs + bv[bj][1];
; #pragma unroll
;                     for (int e = 0; e < 4; ++e) { const float a = fmaxf(v0[e], 0.f), b = fmaxf(v1[e], 0.f); v0[e] = a * a; v1[e] = b * b; }
;                     u32x4 w; w.x = cvt_pk_bf16(v0[0], v0[1]); w.y = cvt_pk_bf16(v0[2], v0[3]); w.z = cvt_pk_bf16(v1[0], v1[1]); w.w = cvt_pk_bf16(v1[2], v1[3]);
;                     *(u32x4*)(rowp + bj * HALF) = w; } }
	s_nop 1
	v_mov_b32_e32 v96, v191
	v_lshlrev_b64 v[100:101], 14, v[130:131]
	v_or_b32_e32 v98, 48, v168
	v_lshl_add_u64 v[100:101], s[16:17], 0, v[100:101]
	v_ashrrev_i32_e32 v99, 31, v98
	v_lshl_add_u64 v[100:101], v[100:101], 0, v[170:171]
	v_lshl_add_u64 v[102:103], v[98:99], 2, s[6:7]
	v_pk_fma_f32 v[94:95], v[94:95], v[96:97], v[126:127] op_sel_hi:[1,0,1]
	v_pk_fma_f32 v[92:93], v[92:93], v[96:97], v[124:125] op_sel_hi:[1,0,1]
	v_pk_fma_f32 v[90:91], v[90:91], v[96:97], v[122:123] op_sel_hi:[1,0,1]
	v_pk_fma_f32 v[88:89], v[88:89], v[96:97], v[120:121] op_sel_hi:[1,0,1]
	v_pk_fma_f32 v[82:83], v[82:83], v[96:97], v[114:115] op_sel_hi:[1,0,1]
	v_pk_fma_f32 v[80:81], v[80:81], v[96:97], v[112:113] op_sel_hi:[1,0,1]
	v_pk_fma_f32 v[86:87], v[86:87], v[96:97], v[118:119] op_sel_hi:[1,0,1]
	v_pk_fma_f32 v[84:85], v[84:85], v[96:97], v[116:117] op_sel_hi:[1,0,1]
	v_max_f32_e32 v92, 0, v92
	v_max_f32_e32 v88, 0, v88
	v_max_f32_e32 v93, 0, v93
	v_max_f32_e32 v89, 0, v89
	v_max_f32_e32 v94, 0, v94
	v_max_f32_e32 v90, 0, v90
	v_max_f32_e32 v95, 0, v95
	v_max_f32_e32 v91, 0, v91
	v_max_f32_e32 v80, 0, v80
	v_max_f32_e32 v81, 0, v81
	v_max_f32_e32 v82, 0, v82
	v_max_f32_e32 v83, 0, v83
	v_max_f32_e32 v84, 0, v84
	v_max_f32_e32 v85, 0, v85
	v_max_f32_e32 v86, 0, v86
	v_max_f32_e32 v87, 0, v87
	v_mul_f32_e32 v92, v92, v92
	v_mul_f32_e32 v88, v88, v88
	v_mul_f32_e32 v93, v93, v93
	v_mul_f32_e32 v89, v89, v89
	v_mul_f32_e32 v94, v94, v94
	v_mul_f32_e32 v90, v90, v90
	v_mul_f32_e32 v95, v95, v95
	v_mul_f32_e32 v91, v91, v91
	v_mul_f32_e32 v96, v80, v80
	v_mul_f32_e32 v97, v81, v81
	v_mul_f32_e32 v104, v82, v82
	v_mul_f32_e32 v105, v83, v83
	v_cvt_pk_bf16_f32 v80, v92, v93
	v_cvt_pk_bf16_f32 v81, v94, v95
	v_cvt_pk_bf16_f32 v82, v88, v89
	v_cvt_pk_bf16_f32 v83, v90, v91
	v_mul_f32_e32 v84, v84, v84
	v_mul_f32_e32 v85, v85, v85
	v_mul_f32_e32 v86, v86, v86
	v_mul_f32_e32 v87, v87, v87
	global_store_dwordx4 v[100:101], v[80:83], off
	s_nop 1
	v_cvt_pk_bf16_f32 v80, v84, v85
	v_cvt_pk_bf16_f32 v81, v86, v87
	v_cvt_pk_bf16_f32 v82, v96, v97
	v_cvt_pk_bf16_f32 v83, v104, v105
	global_store_dwordx4 v[100:101], v[80:83], off offset:256
	s_nop 1
	v_mov_b32_e32 v80, v192
	v_pk_fma_f32 v[78:79], v[78:79], v[80:81], v[126:127] op_sel_hi:[1,0,1]
	v_lshlrev_b64 v[82:83], 14, v[98:99]
	v_pk_fma_f32 v[76:77], v[76:77], v[80:81], v[124:125] op_sel_hi:[1,0,1]
	v_pk_fma_f32 v[74:75], v[74:75], v[80:81], v[122:123] op_sel_hi:[1,0,1]
	v_pk_fma_f32 v[72:73], v[72:73], v[80:81], v[120:121] op_sel_hi:[1,0,1]
	v_pk_fma_f32 v[66:67], v[66:67], v[80:81], v[114:115] op_sel_hi:[1,0,1]
	v_pk_fma_f32 v[64:65], v[64:65], v[80:81], v[112:113] op_sel_hi:[1,0,1]
	v_lshl_add_u64 v[82:83], s[16:17], 0, v[82:83]
	v_pk_fma_f32 v[70:71], v[70:71], v[80:81], v[118:119] op_sel_hi:[1,0,1]
	v_pk_fma_f32 v[68:69], v[68:69], v[80:81], v[116:117] op_sel_hi:[1,0,1]
	v_max_f32_e32 v76, 0, v76
	v_max_f32_e32 v72, 0, v72
	v_max_f32_e32 v77, 0, v77
	v_max_f32_e32 v73, 0, v73
	v_max_f32_e32 v78, 0, v78
	v_max_f32_e32 v74, 0, v74
	v_max_f32_e32 v79, 0, v79
	v_max_f32_e32 v75, 0, v75
	v_max_f32_e32 v64, 0, v64
	v_max_f32_e32 v65, 0, v65
	v_max_f32_e32 v66, 0, v66
	v_max_f32_e32 v67, 0, v67
	v_lshl_add_u64 v[82:83], v[82:83], 0, v[170:171]
	v_max_f32_e32 v68, 0, v68
	v_max_f32_e32 v69, 0, v69
	v_max_f32_e32 v70, 0, v70
	v_max_f32_e32 v71, 0, v71
	v_mul_f32_e32 v76, v76, v76
	v_mul_f32_e32 v72, v72, v72
	v_mul_f32_e32 v77, v77, v77
	v_mul_f32_e32 v73, v73, v73
	v_mul_f32_e32 v78, v78, v78
	v_mul_f32_e32 v74, v74, v74
	v_mul_f32_e32 v79, v79, v79
	v_mul_f32_e32 v75, v75, v75
	v_mul_f32_e32 v80, v64, v64
	v_mul_f32_e32 v81, v65, v65
	v_mul_f32_e32 v84, v66, v66
	v_mul_f32_e32 v85, v67, v67
	v_cvt_pk_bf16_f32 v64, v76, v77
	v_cvt_pk_bf16_f32 v65, v78, v79
	v_cvt_pk_bf16_f32 v66, v72, v73
	v_cvt_pk_bf16_f32 v67, v74, v75
	v_mul_f32_e32 v68, v68, v68
	v_mul_f32_e32 v69, v69, v69
	v_mul_f32_e32 v70, v70, v70
	v_mul_f32_e32 v71, v71, v71
	global_store_dwordx4 v[82:83], v[64:67], off
	s_nop 1
	v_cvt_pk_bf16_f32 v64, v68, v69
	v_cvt_pk_bf16_f32 v65, v70, v71
	v_cvt_pk_bf16_f32 v66, v80, v81
	v_cvt_pk_bf16_f32 v67, v84, v85
	global_store_dwordx4 v[82:83], v[64:67], off offset:256
	s_nop 1
	v_mov_b32_e32 v64, v193
	v_add_co_u32_e32 v68, vcc, s37, v166
	v_lshl_add_u64 v[66:67], v[166:167], 0, s[52:53]
	s_nop 0
	v_addc_co_u32_e32 v69, vcc, 0, v167, vcc
	s_mov_b32 s37, 0x240000
	s_mov_b64 s[52:53], 0x240000
	v_pk_fma_f32 v[62:63], v[62:63], v[64:65], v[126:127] op_sel_hi:[1,0,1]
	v_pk_fma_f32 v[60:61], v[60:61], v[64:65], v[124:125] op_sel_hi:[1,0,1]
	v_pk_fma_f32 v[58:59], v[58:59], v[64:65], v[122:123] op_sel_hi:[1,0,1]
	v_pk_fma_f32 v[56:57], v[56:57], v[64:65], v[120:121] op_sel_hi:[1,0,1]
	v_pk_fma_f32 v[50:51], v[50:51], v[64:65], v[114:115] op_sel_hi:[1,0,1]
	v_pk_fma_f32 v[48:49], v[48:49], v[64:65], v[112:113] op_sel_hi:[1,0,1]
	v_pk_fma_f32 v[54:55], v[54:55], v[64:65], v[118:119] op_sel_hi:[1,0,1]
	v_pk_fma_f32 v[52:53], v[52:53], v[64:65], v[116:117] op_sel_hi:[1,0,1]
	v_max_f32_e32 v60, 0, v60
	v_max_f32_e32 v56, 0, v56
	v_max_f32_e32 v61, 0, v61
	v_max_f32_e32 v57, 0, v57
	v_max_f32_e32 v62, 0, v62
	v_max_f32_e32 v58, 0, v58
	v_max_f32_e32 v63, 0, v63
	v_max_f32_e32 v59, 0, v59
	v_max_f32_e32 v48, 0, v48
	v_max_f32_e32 v49, 0, v49
	v_max_f32_e32 v50, 0, v50
	v_max_f32_e32 v51, 0, v51
	v_max_f32_e32 v52, 0, v52
	v_max_f32_e32 v53, 0, v53
	v_max_f32_e32 v54, 0, v54
	v_max_f32_e32 v55, 0, v55
	v_mul_f32_e32 v60, v60, v60
	v_mul_f32_e32 v56, v56, v56
	v_mul_f32_e32 v61, v61, v61
	v_mul_f32_e32 v57, v57, v57
	v_mul_f32_e32 v62, v62, v62
	v_mul_f32_e32 v58, v58, v58
	v_mul_f32_e32 v63, v63, v63
; __device__ __forceinline__ unsigned cvt_pk_bf16(float lo, float hi) { unsigned r; asm volatile("v_cvt_pk_bf16_f32 %0, %1, %2" : "=v"(r) : "v"(lo), "v"(hi)); return r; }
;     __device__ __forceinline__ void operator()(const f32x4 (&acc)[2][2][4][2], const Unit& u, int wr, int wc, int fr, int fq) const {
;     ...
;             for (int m = 0; m < 4; ++m) { const int row = row0 + ai * HALF + m * 16; bf16_t* rowp = O + (size_t)row * FF + col0; float rs;
;                 if constexpr (SUMP) { const f32x4 p0 = *(const f32x4*)(rstd + (size_t)row * 32 + 8 * fq), p1 = *(const f32x4*)(rstd + (size_t)row * 32 + 8 * fq + 4);
;                     float t = ((p0[0] + p0[1]) + (p0[2] + p0[3])) + ((p1[0] + p1[1]) + (p1[2] + p1[3])); t += __shfl_xor(t, 16); t += __shfl_xor(t, 32); rs = rsqrtf(t * (1.f / D) + EPS); }
;                 else rs = rstd[row];
; #pragma unroll
;                 for (int bj = 0; bj < 2; ++bj) { f32x4 v0 = acc[ai][bj][m][0] * rs + bv[bj][0], v1 = acc[ai][bj][m][1] * rs + bv[bj][1];
; #pragma unroll
;                     for (int e = 0; e < 4; ++e) { const float a = fmaxf(v0[e], 0.f), b = fmaxf(v1[e], 0.f); v0[e] = a * a; v1[e] = b * b; }
;                     u32x4 w; w.x = cvt_pk_bf16(v0[0], v0[1]); w.y = cvt_pk_bf16(v0[2], v0[3]); w.z = cvt_pk_bf16(v1[0], v1[1]); w.w = cvt_pk_bf16(v1[2], v1[3]);
;                     *(u32x4*)(rowp + bj * HALF) = w; } }
	v_mul_f32_e32 v59, v59, v59
	v_mul_f32_e32 v64, v48, v48
	v_mul_f32_e32 v65, v49, v49
	v_mul_f32_e32 v70, v50, v50
	v_mul_f32_e32 v71, v51, v51
	v_cvt_pk_bf16_f32 v48, v60, v61
	v_cvt_pk_bf16_f32 v49, v62, v63
	v_cvt_pk_bf16_f32 v50, v56, v57
	v_cvt_pk_bf16_f32 v51, v58, v59
	v_mul_f32_e32 v52, v52, v52
	v_mul_f32_e32 v53, v53, v53
	v_mul_f32_e32 v54, v54, v54
	v_mul_f32_e32 v55, v55, v55
	global_store_dwordx4 v[68:69], v[48:51], off
	s_nop 1
	v_cvt_pk_bf16_f32 v48, v52, v53
	v_cvt_pk_bf16_f32 v49, v54, v55
	v_cvt_pk_bf16_f32 v50, v64, v65
	v_cvt_pk_bf16_f32 v51, v70, v71
	global_store_dwordx4 v[66:67], v[48:51], off offset:256
	s_nop 1
	v_mov_b32_e32 v48, v194
	v_add_co_u32_e32 v52, vcc, s37, v166
	v_lshl_add_u64 v[50:51], v[166:167], 0, s[52:53]
	s_nop 0
	v_addc_co_u32_e32 v53, vcc, 0, v167, vcc
	s_mov_b32 s37, 0x280000
	s_mov_b64 s[52:53], 0x280000
	v_pk_fma_f32 v[46:47], v[46:47], v[48:49], v[126:127] op_sel_hi:[1,0,1]
	v_pk_fma_f32 v[44:45], v[44:45], v[48:49], v[124:125] op_sel_hi:[1,0,1]
	v_pk_fma_f32 v[42:43], v[42:43], v[48:49], v[122:123] op_sel_hi:[1,0,1]
	v_pk_fma_f32 v[40:41], v[40:41], v[48:49], v[120:121] op_sel_hi:[1,0,1]
	v_pk_fma_f32 v[34:35], v[34:35], v[48:49], v[114:115] op_sel_hi:[1,0,1]
	v_pk_fma_f32 v[32:33], v[32:33], v[48:49], v[112:113] op_sel_hi:[1,0,1]
	v_pk_fma_f32 v[38:39], v[38:39], v[48:49], v[118:119] op_sel_hi:[1,0,1]
	v_pk_fma_f32 v[36:37], v[36:37], v[48:49], v[116:117] op_sel_hi:[1,0,1]
	v_max_f32_e32 v44, 0, v44
	v_max_f32_e32 v40, 0, v40
	v_max_f32_e32 v45, 0, v45
	v_max_f32_e32 v41, 0, v41
	v_max_f32_e32 v46, 0, v46
	v_max_f32_e32 v42, 0, v42
	v_max_f32_e32 v47, 0, v47
	v_max_f32_e32 v43, 0, v43
	v_max_f32_e32 v32, 0, v32
	v_max_f32_e32 v33, 0, v33
	v_max_f32_e32 v34, 0, v34
	v_max_f32_e32 v35, 0, v35
	v_max_f32_e32 v36, 0, v36
	v_max_f32_e32 v37, 0, v37
	v_max_f32_e32 v38, 0, v38
	v_max_f32_e32 v39, 0, v39
	v_mul_f32_e32 v44, v44, v44
	v_mul_f32_e32 v40, v40, v40
	v_mul_f32_e32 v45, v45, v45
	v_mul_f32_e32 v41, v41, v41
	v_mul_f32_e32 v46, v46, v46
	v_mul_f32_e32 v42, v42, v42
	v_mul_f32_e32 v47, v47, v47
	v_mul_f32_e32 v43, v43, v43
	v_mul_f32_e32 v48, v32, v32
	v_mul_f32_e32 v49, v33, v33
	v_mul_f32_e32 v54, v34, v34
	v_mul_f32_e32 v55, v35, v35
	v_cvt_pk_bf16_f32 v32, v44, v45
	v_cvt_pk_bf16_f32 v33, v46, v47
	v_cvt_pk_bf16_f32 v34, v40, v41
	v_cvt_pk_bf16_f32 v35, v42, v43
	v_mul_f32_e32 v36, v36, v36
	v_mul_f32_e32 v37, v37, v37
	v_mul_f32_e32 v38, v38, v38
	v_mul_f32_e32 v39, v39, v39
	global_store_dwordx4 v[52:53], v[32:35], off
	s_nop 1
	v_cvt_pk_bf16_f32 v32, v36, v37
	v_cvt_pk_bf16_f32 v33, v38, v39
	v_cvt_pk_bf16_f32 v34, v48, v49
	v_cvt_pk_bf16_f32 v35, v54, v55
	global_store_dwordx4 v[50:51], v[32:35], off offset:256
	s_nop 1
	v_mov_b32_e32 v32, v195
	v_add_co_u32_e32 v36, vcc, s37, v166
	v_lshl_add_u64 v[34:35], v[166:167], 0, s[52:53]
	s_nop 0
	v_addc_co_u32_e32 v37, vcc, 0, v167, vcc
	s_mov_b32 s37, 0x2c0000
	s_andn2_b64 vcc, exec, s[0:1]
	s_mov_b64 s[52:53], 0x2c0000
	v_pk_fma_f32 v[30:31], v[30:31], v[32:33], v[126:127] op_sel_hi:[1,0,1]
	v_pk_fma_f32 v[28:29], v[28:29], v[32:33], v[124:125] op_sel_hi:[1,0,1]
	v_pk_fma_f32 v[26:27], v[26:27], v[32:33], v[122:123] op_sel_hi:[1,0,1]
	v_pk_fma_f32 v[24:25], v[24:25], v[32:33], v[120:121] op_sel_hi:[1,0,1]
	v_pk_fma_f32 v[18:19], v[18:19], v[32:33], v[114:115] op_sel_hi:[1,0,1]
	v_pk_fma_f32 v[16:17], v[16:17], v[32:33], v[112:113] op_sel_hi:[1,0,1]
	v_pk_fma_f32 v[22:23], v[22:23], v[32:33], v[118:119] op_sel_hi:[1,0,1]
	v_pk_fma_f32 v[20:21], v[20:21], v[32:33], v[116:117] op_sel_hi:[1,0,1]
	v_max_f32_e32 v28, 0, v28
	v_max_f32_e32 v24, 0, v24
	v_max_f32_e32 v29, 0, v29
	v_max_f32_e32 v25, 0, v25
	v_max_f32_e32 v30, 0, v30
	v_max_f32_e32 v26, 0, v26
	v_max_f32_e32 v31, 0, v31
	v_max_f32_e32 v27, 0, v27
	v_max_f32_e32 v16, 0, v16
	v_max_f32_e32 v17, 0, v17
	v_max_f32_e32 v18, 0, v18
	v_max_f32_e32 v19, 0, v19
	v_max_f32_e32 v20, 0, v20
	v_max_f32_e32 v21, 0, v21
	v_max_f32_e32 v22, 0, v22
	v_max_f32_e32 v23, 0, v23
	v_mul_f32_e32 v28, v28, v28
	v_mul_f32_e32 v24, v24, v24
	v_mul_f32_e32 v29, v29, v29
	v_mul_f32_e32 v25, v25, v25
	v_mul_f32_e32 v30, v30, v30
	v_mul_f32_e32 v26, v26, v26
	v_mul_f32_e32 v31, v31, v31
	v_mul_f32_e32 v27, v27, v27
	v_mul_f32_e32 v32, v16, v16
	v_mul_f32_e32 v33, v17, v17
	v_mul_f32_e32 v38, v18, v18
	v_mul_f32_e32 v39, v19, v19
	v_cvt_pk_bf16_f32 v16, v28, v29
	v_cvt_pk_bf16_f32 v17, v30, v31
	v_cvt_pk_bf16_f32 v18, v24, v25
	v_cvt_pk_bf16_f32 v19, v26, v27
	v_mul_f32_e32 v20, v20, v20
	v_mul_f32_e32 v21, v21, v21
	v_mul_f32_e32 v22, v22, v22
	v_mul_f32_e32 v23, v23, v23
	global_store_dwordx4 v[36:37], v[16:19], off
	s_nop 1
	v_cvt_pk_bf16_f32 v16, v20, v21
	v_cvt_pk_bf16_f32 v17, v22, v23
	v_cvt_pk_bf16_f32 v18, v32, v33
	v_cvt_pk_bf16_f32 v19, v38, v39
	global_store_dwordx4 v[34:35], v[16:19], off offset:256
	s_nop 1
	v_mov_b32_e32 v16, v196
	v_add_co_u32_e64 v20, s[0:1], s37, v166
	v_lshl_add_u64 v[18:19], v[166:167], 0, s[52:53]
	s_nop 0
	v_addc_co_u32_e64 v21, s[0:1], 0, v167, s[0:1]
	s_mov_b64 s[0:1], -1
	v_pk_fma_f32 v[14:15], v[14:15], v[16:17], v[126:127] op_sel_hi:[1,0,1]
	v_pk_fma_f32 v[12:13], v[12:13], v[16:17], v[124:125] op_sel_hi:[1,0,1]
	v_pk_fma_f32 v[10:11], v[10:11], v[16:17], v[122:123] op_sel_hi:[1,0,1]
	v_pk_fma_f32 v[8:9], v[8:9], v[16:17], v[120:121] op_sel_hi:[1,0,1]
	v_pk_fma_f32 v[2:3], v[2:3], v[16:17], v[114:115] op_sel_hi:[1,0,1]
	v_pk_fma_f32 v[0:1], v[0:1], v[16:17], v[112:113] op_sel_hi:[1,0,1]
	v_pk_fma_f32 v[6:7], v[6:7], v[16:17], v[118:119] op_sel_hi:[1,0,1]
	v_pk_fma_f32 v[4:5], v[4:5], v[16:17], v[116:117] op_sel_hi:[1,0,1]
	v_max_f32_e32 v12, 0, v12
	v_max_f32_e32 v8, 0, v8
	v_max_f32_e32 v13, 0, v13
	v_max_f32_e32 v9, 0, v9
	v_max_f32_e32 v14, 0, v14
	v_max_f32_e32 v10, 0, v10
	v_max_f32_e32 v15, 0, v15
	v_max_f32_e32 v11, 0, v11
	v_max_f32_e32 v0, 0, v0
	v_max_f32_e32 v1, 0, v1
	v_max_f32_e32 v2, 0, v2
	v_max_f32_e32 v3, 0, v3
	v_max_f32_e32 v4, 0, v4
	v_max_f32_e32 v5, 0, v5
	v_max_f32_e32 v6, 0, v6
	v_max_f32_e32 v7, 0, v7
	v_mul_f32_e32 v12, v12, v12
	v_mul_f32_e32 v8, v8, v8
	v_mul_f32_e32 v13, v13, v13
	v_mul_f32_e32 v9, v9, v9
	v_mul_f32_e32 v14, v14, v14
	v_mul_f32_e32 v10, v10, v10
	v_mul_f32_e32 v15, v15, v15
	v_mul_f32_e32 v11, v11, v11
	v_mul_f32_e32 v16, v0, v0
	v_mul_f32_e32 v17, v1, v1
	v_mul_f32_e32 v22, v2, v2
	v_mul_f32_e32 v23, v3, v3
	v_cvt_pk_bf16_f32 v0, v12, v13
	v_cvt_pk_bf16_f32 v1, v14, v15
	v_cvt_pk_bf16_f32 v2, v8, v9
	v_cvt_pk_bf16_f32 v3, v10, v11
	v_mul_f32_e32 v4, v4, v4
	v_mul_f32_e32 v5, v5, v5
	v_mul_f32_e32 v6, v6, v6
	v_mul_f32_e32 v7, v7, v7
	global_store_dwordx4 v[20:21], v[0:3], off
	s_nop 1
	v_cvt_pk_bf16_f32 v0, v4, v5
	v_cvt_pk_bf16_f32 v1, v6, v7
	v_cvt_pk_bf16_f32 v2, v16, v17
	v_cvt_pk_bf16_f32 v3, v22, v23
	global_store_dwordx4 v[18:19], v[0:3], off offset:256
	s_cbranch_vccnz .LBB0_541
	s_andn2_b64 vcc, exec, s[10:11]
	s_cbranch_vccnz .LBB0_540
	s_barrier
	s_branch .LBB0_540

; __device__ __forceinline__ unsigned cvt_pk_bf16(float lo, float hi) { unsigned r; asm volatile("v_cvt_pk_bf16_f32 %0, %1, %2" : "=v"(r) : "v"(lo), "v"(hi)); return r; }
;     __device__ __forceinline__ void operator()(const f32x4 (&acc)[2][2][4][2], const Unit& u, int wr, int wc, int fr, int fq) const {
;         const int row0 = u.pm * BM + wr * 64 + fr, col0 = u.pn * BM + wc * 32 + 8 * fq;
;         const int mr = u.pm < (ML / BM) ? u.pm / (SEQ / BM) : BATCH;
;         f32x4 bv[2][2];
; #pragma unroll
;         for (int bj = 0; bj < 2; ++bj)
; #pragma unroll
;             for (int n = 0; n < 2; ++n) bv[bj][n] = *(const f32x4*)(shw + (size_t)mr * FF + col0 + bj * HALF + 4 * n);
; #pragma unroll
;         for (int ai = 0; ai < 2; ++ai)
; #pragma unroll
;             for (int m = 0; m < 4; ++m) { const int row = row0 + ai * HALF + m * 16; bf16_t* rowp = O + (size_t)row * FF + col0; float rs;
;                 if constexpr (SUMP) { const f32x4 p0 = *(const f32x4*)(rstd + (size_t)row * 32 + 8 * fq), p1 = *(const f32x4*)(rstd + (size_t)row * 32 + 8 * fq + 4);
;                     float t = ((p0[0] + p0[1]) + (p0[2] + p0[3])) + ((p1[0] + p1[1]) + (p1[2] + p1[3])); t += __shfl_xor(t, 16); t += __shfl_xor(t, 32); rs = rsqrtf(t * (1.f / D) + EPS); }
;                 else rs = rstd[row];
; #pragma unroll
;                 for (int bj = 0; bj < 2; ++bj) { f32x4 v0 = acc[ai][bj][m][0] * rs + bv[bj][0], v1 = acc[ai][bj][m][1] * rs + bv[bj][1];
; #pragma unroll
;                     for (int e = 0; e < 4; ++e) { const float a = fmaxf(v0[e], 0.f), b = fmaxf(v1[e], 0.f); v0[e] = a * a; v1[e] = b * b; }
;                     u32x4 w; w.x = cvt_pk_bf16(v0[0], v0[1]); w.y = cvt_pk_bf16(v0[2], v0[3]); w.z = cvt_pk_bf16(v1[0], v1[1]); w.w = cvt_pk_bf16(v1[2], v1[3]);
;                     *(u32x4*)(rowp + bj * HALF) = w; } }
.LBB0_1147:
	v_lshl_add_u32 v166, s40, 8, v168
	v_ashrrev_i32_e32 v167, 31, v166
	v_lshlrev_b64 v[80:81], 7, v[166:167]
	v_lshl_add_u64 v[80:81], v[154:155], 0, v[80:81]
	global_load_dwordx4 v[178:181], v[80:81], off
	global_load_dwordx4 v[182:185], v[80:81], off offset:16
	global_load_dwordx4 v[190:193], v[80:81], off offset:2048
	global_load_dwordx4 v[194:197], v[80:81], off offset:2064
	v_mov_b64_e32 v[246:247], 0x1000
	v_lshl_add_u64 v[250:251], v[80:81], 0, v[246:247]
	global_load_dwordx4 v[198:201], v[250:251], off
	global_load_dwordx4 v[202:205], v[250:251], off offset:16
	global_load_dwordx4 v[206:209], v[250:251], off offset:2048
	global_load_dwordx4 v[210:213], v[250:251], off offset:2064
	v_mov_b64_e32 v[246:247], 0x4000
	v_lshl_add_u64 v[250:251], v[80:81], 0, v[246:247]
	global_load_dwordx4 v[214:217], v[250:251], off
	global_load_dwordx4 v[218:221], v[250:251], off offset:16
	global_load_dwordx4 v[222:225], v[250:251], off offset:2048
	global_load_dwordx4 v[226:229], v[250:251], off offset:2064
	v_mov_b64_e32 v[246:247], 0x5000
	v_lshl_add_u64 v[250:251], v[80:81], 0, v[246:247]
	global_load_dwordx4 v[230:233], v[250:251], off
	global_load_dwordx4 v[234:237], v[250:251], off offset:16
	global_load_dwordx4 v[238:241], v[250:251], off offset:2048
	global_load_dwordx4 v[242:245], v[250:251], off offset:2064
	s_lshl_b64 s[42:43], s[42:43], 2
	v_lshl_or_b32 v164, s59, 8, v170
	s_add_u32 s42, s72, s42
	v_ashrrev_i32_e32 v165, 31, v164
	s_addc_u32 s43, s73, s43
	v_lshl_add_u64 v[80:81], v[164:165], 2, s[42:43]
	global_load_dwordx4 v[92:95], v[80:81], off
	global_load_dwordx4 v[88:91], v[80:81], off offset:16
	global_load_dwordx4 v[84:87], v[80:81], off offset:512
	s_nop 0
	global_load_dwordx4 v[80:83], v[80:81], off offset:528
	v_and_b32_e32 v177, 64, v174
	v_xor_b32_e32 v176, 16, v174
	v_add_u32_e32 v177, 64, v177
	v_cmp_lt_i32_e32 vcc, v176, v177
	v_xor_b32_e32 v188, 32, v174
	v_lshlrev_b64 v[164:165], 1, v[164:165]
	v_cndmask_b32_e32 v176, v174, v176, vcc
	v_lshlrev_b32_e32 v176, 2, v176
	v_cmp_lt_i32_e32 vcc, v188, v177
	s_waitcnt vmcnt(0)
	v_mov_b32_e32 v186, v178
	v_mov_b32_e32 v187, v182
	v_mov_b32_e32 v182, v179
	v_mov_b32_e32 v178, v180
	v_mov_b32_e32 v179, v184
	v_mov_b32_e32 v184, v181
	v_pk_add_f32 v[180:181], v[186:187], v[182:183]
	v_pk_add_f32 v[178:179], v[178:179], v[184:185]
	v_cndmask_b32_e32 v177, v174, v188, vcc
	v_pk_add_f32 v[178:179], v[180:181], v[178:179]
	v_lshlrev_b32_e32 v177, 2, v177
	v_add_f32_e32 v179, v178, v179
	ds_bpermute_b32 v180, v176, v179
	v_or_b32_e32 v178, 16, v166
	s_waitcnt lgkmcnt(0)
	v_add_f32_e32 v182, v179, v180
	ds_bpermute_b32 v183, v177, v182
	v_lshlrev_b64 v[180:181], 14, v[166:167]
	v_ashrrev_i32_e32 v179, 31, v178
	v_lshl_add_u64 v[180:181], s[16:17], 0, v[180:181]
	v_lshl_add_u64 v[180:181], v[180:181], 0, v[164:165]
	s_waitcnt lgkmcnt(0)
	v_add_f32_e32 v167, v182, v183
	v_fmamk_f32 v167, v167, 0x3a000000, v175
	v_mul_f32_e32 v182, 0x4b800000, v167
	v_cmp_gt_f32_e32 vcc, s58, v167
	s_nop 1
	v_cndmask_b32_e32 v167, v167, v182, vcc
	v_rsq_f32_e32 v167, v167
	v_lshlrev_b64 v[182:183], 7, v[178:179]
	v_lshl_add_u64 v[182:183], v[154:155], 0, v[182:183]
	v_mul_f32_e32 v184, 0x45800000, v167
	v_cndmask_b32_e32 v184, v167, v184, vcc
	v_pk_fma_f32 v[142:143], v[142:143], v[184:185], v[94:95] op_sel_hi:[1,0,1]
	v_pk_fma_f32 v[140:141], v[140:141], v[184:185], v[92:93] op_sel_hi:[1,0,1]
	v_pk_fma_f32 v[138:139], v[138:139], v[184:185], v[90:91] op_sel_hi:[1,0,1]
	v_pk_fma_f32 v[136:137], v[136:137], v[184:185], v[88:89] op_sel_hi:[1,0,1]
	v_pk_fma_f32 v[130:131], v[130:131], v[184:185], v[82:83] op_sel_hi:[1,0,1]
	v_pk_fma_f32 v[128:129], v[128:129], v[184:185], v[80:81] op_sel_hi:[1,0,1]
	v_pk_fma_f32 v[134:135], v[134:135], v[184:185], v[86:87] op_sel_hi:[1,0,1]
	v_pk_fma_f32 v[132:133], v[132:133], v[184:185], v[84:85] op_sel_hi:[1,0,1]
	v_max_f32_e32 v140, 0, v140
	v_max_f32_e32 v136, 0, v136
	v_max_f32_e32 v141, 0, v141
	v_max_f32_e32 v137, 0, v137
	v_max_f32_e32 v142, 0, v142
	v_max_f32_e32 v138, 0, v138
	v_max_f32_e32 v143, 0, v143
	v_max_f32_e32 v139, 0, v139
	v_max_f32_e32 v128, 0, v128
	v_max_f32_e32 v129, 0, v129
	v_max_f32_e32 v130, 0, v130
	v_max_f32_e32 v131, 0, v131
	v_max_f32_e32 v132, 0, v132
	v_max_f32_e32 v133, 0, v133
	v_max_f32_e32 v134, 0, v134
	v_max_f32_e32 v135, 0, v135
	v_mul_f32_e32 v140, v140, v140
	v_mul_f32_e32 v136, v136, v136
	v_mul_f32_e32 v141, v141, v141
	v_mul_f32_e32 v137, v137, v137
	v_mul_f32_e32 v142, v142, v142
	v_mul_f32_e32 v138, v138, v138
	v_mul_f32_e32 v143, v143, v143
	v_mul_f32_e32 v139, v139, v139
	v_mul_f32_e32 v167, v128, v128
	v_mul_f32_e32 v184, v129, v129
	v_mul_f32_e32 v185, v130, v130
	v_mul_f32_e32 v186, v131, v131
	v_cvt_pk_bf16_f32 v128, v140, v141
	v_cvt_pk_bf16_f32 v129, v142, v143
	v_cvt_pk_bf16_f32 v130, v136, v137
	v_cvt_pk_bf16_f32 v131, v138, v139
	v_mul_f32_e32 v132, v132, v132
	v_mul_f32_e32 v133, v133, v133
	v_mul_f32_e32 v134, v134, v134
	v_mul_f32_e32 v135, v135, v135
	global_store_dwordx4 v[180:181], v[128:131], off
	s_nop 1
	v_cvt_pk_bf16_f32 v128, v132, v133
	v_cvt_pk_bf16_f32 v129, v134, v135
	v_cvt_pk_bf16_f32 v130, v167, v184
	v_cvt_pk_bf16_f32 v131, v185, v186
	global_store_dwordx4 v[180:181], v[128:131], off offset:256
	s_nop 1
	v_mov_b64_e32 v[128:129], v[190:191]
	v_mov_b64_e32 v[130:131], v[192:193]
	v_mov_b64_e32 v[132:133], v[194:195]
	v_mov_b64_e32 v[134:135], v[196:197]
	v_mov_b32_e32 v136, v128
	v_mov_b32_e32 v137, v132
	v_mov_b32_e32 v132, v129
	v_mov_b32_e32 v128, v130
	v_mov_b32_e32 v129, v134
	v_mov_b32_e32 v134, v131
	v_pk_add_f32 v[130:131], v[136:137], v[132:133]
	v_pk_add_f32 v[128:129], v[128:129], v[134:135]
	s_nop 0
	v_pk_add_f32 v[128:129], v[130:131], v[128:129]
	v_lshlrev_b64 v[130:131], 14, v[178:179]
	v_add_f32_e32 v128, v128, v129
	ds_bpermute_b32 v129, v176, v128
	v_lshl_add_u64 v[130:131], s[16:17], 0, v[130:131]
	v_lshl_add_u64 v[130:131], v[130:131], 0, v[164:165]
	s_waitcnt lgkmcnt(0)
; __device__ __forceinline__ unsigned cvt_pk_bf16(float lo, float hi) { unsigned r; asm volatile("v_cvt_pk_bf16_f32 %0, %1, %2" : "=v"(r) : "v"(lo), "v"(hi)); return r; }
;     __device__ __forceinline__ void operator()(const f32x4 (&acc)[2][2][4][2], const Unit& u, int wr, int wc, int fr, int fq) const {
;     ...
;             for (int m = 0; m < 4; ++m) { const int row = row0 + ai * HALF + m * 16; bf16_t* rowp = O + (size_t)row * FF + col0; float rs;
;                 if constexpr (SUMP) { const f32x4 p0 = *(const f32x4*)(rstd + (size_t)row * 32 + 8 * fq), p1 = *(const f32x4*)(rstd + (size_t)row * 32 + 8 * fq + 4);
;                     float t = ((p0[0] + p0[1]) + (p0[2] + p0[3])) + ((p1[0] + p1[1]) + (p1[2] + p1[3])); t += __shfl_xor(t, 16); t += __shfl_xor(t, 32); rs = rsqrtf(t * (1.f / D) + EPS); }
;                 else rs = rstd[row];
; #pragma unroll
;                 for (int bj = 0; bj < 2; ++bj) { f32x4 v0 = acc[ai][bj][m][0] * rs + bv[bj][0], v1 = acc[ai][bj][m][1] * rs + bv[bj][1];
; #pragma unroll
;                     for (int e = 0; e < 4; ++e) { const float a = fmaxf(v0[e], 0.f), b = fmaxf(v1[e], 0.f); v0[e] = a * a; v1[e] = b * b; }
;                     u32x4 w; w.x = cvt_pk_bf16(v0[0], v0[1]); w.y = cvt_pk_bf16(v0[2], v0[3]); w.z = cvt_pk_bf16(v1[0], v1[1]); w.w = cvt_pk_bf16(v1[2], v1[3]);
;                     *(u32x4*)(rowp + bj * HALF) = w; } }
	v_add_f32_e32 v134, v128, v129
	ds_bpermute_b32 v135, v177, v134
	v_or_b32_e32 v128, 32, v166
	v_ashrrev_i32_e32 v129, 31, v128
	v_lshlrev_b64 v[132:133], 7, v[128:129]
	v_lshl_add_u64 v[132:133], v[154:155], 0, v[132:133]
	s_waitcnt lgkmcnt(0)
	v_add_f32_e32 v134, v134, v135
	v_fmamk_f32 v134, v134, 0x3a000000, v175
	v_mul_f32_e32 v135, 0x4b800000, v134
	v_cmp_gt_f32_e32 vcc, s58, v134
	s_nop 1
	v_cndmask_b32_e32 v134, v134, v135, vcc
	v_rsq_f32_e32 v134, v134
	s_nop 0
	v_mul_f32_e32 v135, 0x45800000, v134
	v_cndmask_b32_e32 v134, v134, v135, vcc
	v_pk_fma_f32 v[126:127], v[126:127], v[134:135], v[94:95] op_sel_hi:[1,0,1]
	v_pk_fma_f32 v[124:125], v[124:125], v[134:135], v[92:93] op_sel_hi:[1,0,1]
	v_pk_fma_f32 v[122:123], v[122:123], v[134:135], v[90:91] op_sel_hi:[1,0,1]
	v_pk_fma_f32 v[120:121], v[120:121], v[134:135], v[88:89] op_sel_hi:[1,0,1]
	v_pk_fma_f32 v[114:115], v[114:115], v[134:135], v[82:83] op_sel_hi:[1,0,1]
	v_pk_fma_f32 v[112:113], v[112:113], v[134:135], v[80:81] op_sel_hi:[1,0,1]
	v_pk_fma_f32 v[118:119], v[118:119], v[134:135], v[86:87] op_sel_hi:[1,0,1]
	v_pk_fma_f32 v[116:117], v[116:117], v[134:135], v[84:85] op_sel_hi:[1,0,1]
	v_max_f32_e32 v124, 0, v124
	v_max_f32_e32 v120, 0, v120
	v_max_f32_e32 v125, 0, v125
	v_max_f32_e32 v121, 0, v121
	v_max_f32_e32 v126, 0, v126
	v_max_f32_e32 v122, 0, v122
	v_max_f32_e32 v127, 0, v127
	v_max_f32_e32 v123, 0, v123
	v_max_f32_e32 v112, 0, v112
	v_max_f32_e32 v113, 0, v113
	v_max_f32_e32 v114, 0, v114
	v_max_f32_e32 v115, 0, v115
	v_max_f32_e32 v116, 0, v116
	v_max_f32_e32 v117, 0, v117
	v_max_f32_e32 v118, 0, v118
	v_max_f32_e32 v119, 0, v119
	v_mul_f32_e32 v124, v124, v124
	v_mul_f32_e32 v120, v120, v120
	v_mul_f32_e32 v125, v125, v125
	v_mul_f32_e32 v121, v121, v121
	v_mul_f32_e32 v126, v126, v126
	v_mul_f32_e32 v122, v122, v122
	v_mul_f32_e32 v127, v127, v127
	v_mul_f32_e32 v123, v123, v123
	v_mul_f32_e32 v134, v112, v112
	v_mul_f32_e32 v135, v113, v113
	v_mul_f32_e32 v136, v114, v114
	v_mul_f32_e32 v137, v115, v115
	v_cvt_pk_bf16_f32 v112, v124, v125
	v_cvt_pk_bf16_f32 v113, v126, v127
	v_cvt_pk_bf16_f32 v114, v120, v121
	v_cvt_pk_bf16_f32 v115, v122, v123
	v_mul_f32_e32 v116, v116, v116
	v_mul_f32_e32 v117, v117, v117
	v_mul_f32_e32 v118, v118, v118
	v_mul_f32_e32 v119, v119, v119
	global_store_dwordx4 v[130:131], v[112:115], off
	s_nop 1
	v_cvt_pk_bf16_f32 v112, v116, v117
	v_cvt_pk_bf16_f32 v113, v118, v119
	v_cvt_pk_bf16_f32 v114, v134, v135
	v_cvt_pk_bf16_f32 v115, v136, v137
	global_store_dwordx4 v[130:131], v[112:115], off offset:256
	s_nop 1
	v_mov_b64_e32 v[112:113], v[198:199]
	v_mov_b64_e32 v[114:115], v[200:201]
	v_mov_b64_e32 v[116:117], v[202:203]
	v_mov_b64_e32 v[118:119], v[204:205]
	v_mov_b32_e32 v120, v112
	v_mov_b32_e32 v121, v116
	v_mov_b32_e32 v116, v113
	v_mov_b32_e32 v112, v114
	v_mov_b32_e32 v113, v118
	v_mov_b32_e32 v118, v115
	v_pk_add_f32 v[114:115], v[120:121], v[116:117]
	v_pk_add_f32 v[112:113], v[112:113], v[118:119]
	s_nop 0
	v_pk_add_f32 v[112:113], v[114:115], v[112:113]
	v_lshlrev_b64 v[114:115], 14, v[128:129]
	v_add_f32_e32 v112, v112, v113
	ds_bpermute_b32 v113, v176, v112
	v_lshl_add_u64 v[114:115], s[16:17], 0, v[114:115]
	v_lshl_add_u64 v[114:115], v[114:115], 0, v[164:165]
	s_waitcnt lgkmcnt(0)
	v_add_f32_e32 v118, v112, v113
	ds_bpermute_b32 v119, v177, v118
	v_or_b32_e32 v112, 48, v166
	v_ashrrev_i32_e32 v113, 31, v112
	v_lshlrev_b64 v[116:117], 7, v[112:113]
	v_lshl_add_u64 v[116:117], v[154:155], 0, v[116:117]
	s_waitcnt lgkmcnt(0)
	v_add_f32_e32 v118, v118, v119
	v_fmamk_f32 v118, v118, 0x3a000000, v175
	v_mul_f32_e32 v119, 0x4b800000, v118
	v_cmp_gt_f32_e32 vcc, s58, v118
	s_nop 1
	v_cndmask_b32_e32 v118, v118, v119, vcc
	v_rsq_f32_e32 v118, v118
	s_nop 0
	v_mul_f32_e32 v119, 0x45800000, v118
	v_cndmask_b32_e32 v118, v118, v119, vcc
	v_pk_fma_f32 v[110:111], v[110:111], v[118:119], v[94:95] op_sel_hi:[1,0,1]
	v_pk_fma_f32 v[108:109], v[108:109], v[118:119], v[92:93] op_sel_hi:[1,0,1]
	v_pk_fma_f32 v[106:107], v[106:107], v[118:119], v[90:91] op_sel_hi:[1,0,1]
	v_pk_fma_f32 v[104:105], v[104:105], v[118:119], v[88:89] op_sel_hi:[1,0,1]
	v_pk_fma_f32 v[98:99], v[98:99], v[118:119], v[82:83] op_sel_hi:[1,0,1]
	v_pk_fma_f32 v[96:97], v[96:97], v[118:119], v[80:81] op_sel_hi:[1,0,1]
	v_pk_fma_f32 v[102:103], v[102:103], v[118:119], v[86:87] op_sel_hi:[1,0,1]
	v_pk_fma_f32 v[100:101], v[100:101], v[118:119], v[84:85] op_sel_hi:[1,0,1]
	v_max_f32_e32 v108, 0, v108
	v_max_f32_e32 v104, 0, v104
	v_max_f32_e32 v109, 0, v109
	v_max_f32_e32 v105, 0, v105
	v_max_f32_e32 v110, 0, v110
	v_max_f32_e32 v106, 0, v106
	v_max_f32_e32 v111, 0, v111
	v_max_f32_e32 v107, 0, v107
	v_max_f32_e32 v96, 0, v96
	v_max_f32_e32 v97, 0, v97
	v_max_f32_e32 v98, 0, v98
	v_max_f32_e32 v99, 0, v99
	v_max_f32_e32 v100, 0, v100
	v_max_f32_e32 v101, 0, v101
	v_max_f32_e32 v102, 0, v102
	v_max_f32_e32 v103, 0, v103
	v_mul_f32_e32 v108, v108, v108
	v_mul_f32_e32 v104, v104, v104
	v_mul_f32_e32 v109, v109, v109
	v_mul_f32_e32 v105, v105, v105
	v_mul_f32_e32 v110, v110, v110
	v_mul_f32_e32 v106, v106, v106
	v_mul_f32_e32 v111, v111, v111
	v_mul_f32_e32 v107, v107, v107
	v_mul_f32_e32 v118, v96, v96
	v_mul_f32_e32 v119, v97, v97
	v_mul_f32_e32 v120, v98, v98
	v_mul_f32_e32 v121, v99, v99
	v_cvt_pk_bf16_f32 v96, v108, v109
	v_cvt_pk_bf16_f32 v97, v110, v111
	v_cvt_pk_bf16_f32 v98, v104, v105
	v_cvt_pk_bf16_f32 v99, v106, v107
	v_mul_f32_e32 v100, v100, v100
	v_mul_f32_e32 v101, v101, v101
	v_mul_f32_e32 v102, v102, v102
	v_mul_f32_e32 v103, v103, v103
	global_store_dwordx4 v[114:115], v[96:99], off
	s_nop 1
	v_cvt_pk_bf16_f32 v96, v100, v101
	v_cvt_pk_bf16_f32 v97, v102, v103
	v_cvt_pk_bf16_f32 v98, v118, v119
	v_cvt_pk_bf16_f32 v99, v120, v121
	global_store_dwordx4 v[114:115], v[96:99], off offset:256
	s_nop 1
	v_mov_b64_e32 v[96:97], v[206:207]
	v_mov_b64_e32 v[98:99], v[208:209]
	v_mov_b64_e32 v[100:101], v[210:211]
	v_mov_b64_e32 v[102:103], v[212:213]
	v_mov_b32_e32 v104, v96
	v_mov_b32_e32 v105, v100
	v_mov_b32_e32 v100, v97
	v_mov_b32_e32 v96, v98
	v_mov_b32_e32 v97, v102
	v_mov_b32_e32 v102, v99
	v_pk_add_f32 v[98:99], v[104:105], v[100:101]
	v_pk_add_f32 v[96:97], v[96:97], v[102:103]
	s_nop 0
	v_pk_add_f32 v[96:97], v[98:99], v[96:97]
	v_lshlrev_b64 v[98:99], 14, v[112:113]
	v_add_f32_e32 v96, v96, v97
	ds_bpermute_b32 v97, v176, v96
	v_lshl_add_u64 v[98:99], s[16:17], 0, v[98:99]
	v_lshl_add_u64 v[98:99], v[98:99], 0, v[164:165]
	s_waitcnt lgkmcnt(0)
; __device__ __forceinline__ unsigned cvt_pk_bf16(float lo, float hi) { unsigned r; asm volatile("v_cvt_pk_bf16_f32 %0, %1, %2" : "=v"(r) : "v"(lo), "v"(hi)); return r; }
;     __device__ __forceinline__ void operator()(const f32x4 (&acc)[2][2][4][2], const Unit& u, int wr, int wc, int fr, int fq) const {
;     ...
;             for (int m = 0; m < 4; ++m) { const int row = row0 + ai * HALF + m * 16; bf16_t* rowp = O + (size_t)row * FF + col0; float rs;
;                 if constexpr (SUMP) { const f32x4 p0 = *(const f32x4*)(rstd + (size_t)row * 32 + 8 * fq), p1 = *(const f32x4*)(rstd + (size_t)row * 32 + 8 * fq + 4);
;                     float t = ((p0[0] + p0[1]) + (p0[2] + p0[3])) + ((p1[0] + p1[1]) + (p1[2] + p1[3])); t += __shfl_xor(t, 16); t += __shfl_xor(t, 32); rs = rsqrtf(t * (1.f / D) + EPS); }
;                 else rs = rstd[row];
; #pragma unroll
;                 for (int bj = 0; bj < 2; ++bj) { f32x4 v0 = acc[ai][bj][m][0] * rs + bv[bj][0], v1 = acc[ai][bj][m][1] * rs + bv[bj][1];
; #pragma unroll
;                     for (int e = 0; e < 4; ++e) { const float a = fmaxf(v0[e], 0.f), b = fmaxf(v1[e], 0.f); v0[e] = a * a; v1[e] = b * b; }
;                     u32x4 w; w.x = cvt_pk_bf16(v0[0], v0[1]); w.y = cvt_pk_bf16(v0[2], v0[3]); w.z = cvt_pk_bf16(v1[0], v1[1]); w.w = cvt_pk_bf16(v1[2], v1[3]);
;                     *(u32x4*)(rowp + bj * HALF) = w; } }
	v_add_f32_e32 v102, v96, v97
	ds_bpermute_b32 v103, v177, v102
	v_add_u32_e32 v96, 0x80, v166
	v_ashrrev_i32_e32 v97, 31, v96
	v_lshlrev_b64 v[100:101], 7, v[96:97]
	v_lshl_add_u64 v[100:101], v[154:155], 0, v[100:101]
	s_waitcnt lgkmcnt(0)
	v_add_f32_e32 v102, v102, v103
	v_fmamk_f32 v102, v102, 0x3a000000, v175
	v_mul_f32_e32 v103, 0x4b800000, v102
	v_cmp_gt_f32_e32 vcc, s58, v102
	s_nop 1
	v_cndmask_b32_e32 v102, v102, v103, vcc
	v_rsq_f32_e32 v102, v102
	s_nop 0
	v_mul_f32_e32 v103, 0x45800000, v102
	v_cndmask_b32_e32 v102, v102, v103, vcc
	v_pk_fma_f32 v[78:79], v[78:79], v[102:103], v[94:95] op_sel_hi:[1,0,1]
	v_pk_fma_f32 v[76:77], v[76:77], v[102:103], v[92:93] op_sel_hi:[1,0,1]
	v_pk_fma_f32 v[74:75], v[74:75], v[102:103], v[90:91] op_sel_hi:[1,0,1]
	v_pk_fma_f32 v[72:73], v[72:73], v[102:103], v[88:89] op_sel_hi:[1,0,1]
	v_pk_fma_f32 v[66:67], v[66:67], v[102:103], v[82:83] op_sel_hi:[1,0,1]
	v_pk_fma_f32 v[64:65], v[64:65], v[102:103], v[80:81] op_sel_hi:[1,0,1]
	v_pk_fma_f32 v[70:71], v[70:71], v[102:103], v[86:87] op_sel_hi:[1,0,1]
	v_pk_fma_f32 v[68:69], v[68:69], v[102:103], v[84:85] op_sel_hi:[1,0,1]
	v_max_f32_e32 v76, 0, v76
	v_max_f32_e32 v72, 0, v72
	v_max_f32_e32 v77, 0, v77
	v_max_f32_e32 v73, 0, v73
	v_max_f32_e32 v78, 0, v78
	v_max_f32_e32 v74, 0, v74
	v_max_f32_e32 v79, 0, v79
	v_max_f32_e32 v75, 0, v75
	v_max_f32_e32 v64, 0, v64
	v_max_f32_e32 v65, 0, v65
	v_max_f32_e32 v66, 0, v66
	v_max_f32_e32 v67, 0, v67
	v_max_f32_e32 v68, 0, v68
	v_max_f32_e32 v69, 0, v69
	v_max_f32_e32 v70, 0, v70
	v_max_f32_e32 v71, 0, v71
	v_mul_f32_e32 v76, v76, v76
	v_mul_f32_e32 v72, v72, v72
	v_mul_f32_e32 v77, v77, v77
	v_mul_f32_e32 v73, v73, v73
	v_mul_f32_e32 v78, v78, v78
	v_mul_f32_e32 v74, v74, v74
	v_mul_f32_e32 v79, v79, v79
	v_mul_f32_e32 v75, v75, v75
	v_mul_f32_e32 v102, v64, v64
	v_mul_f32_e32 v103, v65, v65
	v_mul_f32_e32 v104, v66, v66
	v_mul_f32_e32 v105, v67, v67
	v_cvt_pk_bf16_f32 v64, v76, v77
	v_cvt_pk_bf16_f32 v65, v78, v79
	v_cvt_pk_bf16_f32 v66, v72, v73
	v_cvt_pk_bf16_f32 v67, v74, v75
	v_mul_f32_e32 v68, v68, v68
	v_mul_f32_e32 v69, v69, v69
	v_mul_f32_e32 v70, v70, v70
	v_mul_f32_e32 v71, v71, v71
	global_store_dwordx4 v[98:99], v[64:67], off
	s_nop 1
	v_cvt_pk_bf16_f32 v64, v68, v69
	v_cvt_pk_bf16_f32 v65, v70, v71
	v_cvt_pk_bf16_f32 v66, v102, v103
	v_cvt_pk_bf16_f32 v67, v104, v105
	global_store_dwordx4 v[98:99], v[64:67], off offset:256
	s_nop 1
	v_mov_b64_e32 v[64:65], v[214:215]
	v_mov_b64_e32 v[66:67], v[216:217]
	v_mov_b64_e32 v[68:69], v[218:219]
	v_mov_b64_e32 v[70:71], v[220:221]
	v_mov_b32_e32 v72, v64
	v_mov_b32_e32 v73, v68
	v_mov_b32_e32 v68, v65
	v_mov_b32_e32 v64, v66
	v_mov_b32_e32 v65, v70
	v_mov_b32_e32 v70, v67
	v_pk_add_f32 v[66:67], v[72:73], v[68:69]
	v_pk_add_f32 v[64:65], v[64:65], v[70:71]
	s_nop 0
	v_pk_add_f32 v[64:65], v[66:67], v[64:65]
	v_lshlrev_b64 v[66:67], 14, v[96:97]
	v_add_f32_e32 v64, v64, v65
	ds_bpermute_b32 v65, v176, v64
	v_lshl_add_u64 v[66:67], s[16:17], 0, v[66:67]
	v_lshl_add_u64 v[66:67], v[66:67], 0, v[164:165]
	s_waitcnt lgkmcnt(0)
	v_add_f32_e32 v70, v64, v65
	ds_bpermute_b32 v71, v177, v70
	v_add_u32_e32 v64, 0x90, v166
	v_ashrrev_i32_e32 v65, 31, v64
	v_lshlrev_b64 v[68:69], 7, v[64:65]
	v_lshl_add_u64 v[68:69], v[154:155], 0, v[68:69]
	s_waitcnt lgkmcnt(0)
	v_add_f32_e32 v70, v70, v71
	v_fmamk_f32 v70, v70, 0x3a000000, v175
	v_mul_f32_e32 v71, 0x4b800000, v70
	v_cmp_gt_f32_e32 vcc, s58, v70
	s_nop 1
	v_cndmask_b32_e32 v70, v70, v71, vcc
	v_rsq_f32_e32 v70, v70
	s_nop 0
	v_mul_f32_e32 v71, 0x45800000, v70
	v_cndmask_b32_e32 v70, v70, v71, vcc
	v_pk_fma_f32 v[62:63], v[62:63], v[70:71], v[94:95] op_sel_hi:[1,0,1]
	v_pk_fma_f32 v[60:61], v[60:61], v[70:71], v[92:93] op_sel_hi:[1,0,1]
	v_pk_fma_f32 v[58:59], v[58:59], v[70:71], v[90:91] op_sel_hi:[1,0,1]
	v_pk_fma_f32 v[56:57], v[56:57], v[70:71], v[88:89] op_sel_hi:[1,0,1]
	v_pk_fma_f32 v[50:51], v[50:51], v[70:71], v[82:83] op_sel_hi:[1,0,1]
	v_pk_fma_f32 v[48:49], v[48:49], v[70:71], v[80:81] op_sel_hi:[1,0,1]
	v_pk_fma_f32 v[54:55], v[54:55], v[70:71], v[86:87] op_sel_hi:[1,0,1]
	v_pk_fma_f32 v[52:53], v[52:53], v[70:71], v[84:85] op_sel_hi:[1,0,1]
	v_max_f32_e32 v60, 0, v60
	v_max_f32_e32 v56, 0, v56
	v_max_f32_e32 v61, 0, v61
	v_max_f32_e32 v57, 0, v57
	v_max_f32_e32 v62, 0, v62
	v_max_f32_e32 v58, 0, v58
	v_max_f32_e32 v63, 0, v63
	v_max_f32_e32 v59, 0, v59
	v_max_f32_e32 v48, 0, v48
	v_max_f32_e32 v49, 0, v49
	v_max_f32_e32 v50, 0, v50
	v_max_f32_e32 v51, 0, v51
	v_max_f32_e32 v52, 0, v52
	v_max_f32_e32 v53, 0, v53
	v_max_f32_e32 v54, 0, v54
	v_max_f32_e32 v55, 0, v55
	v_mul_f32_e32 v60, v60, v60
	v_mul_f32_e32 v56, v56, v56
	v_mul_f32_e32 v61, v61, v61
	v_mul_f32_e32 v57, v57, v57
	v_mul_f32_e32 v62, v62, v62
	v_mul_f32_e32 v58, v58, v58
	v_mul_f32_e32 v63, v63, v63
	v_mul_f32_e32 v59, v59, v59
	v_mul_f32_e32 v70, v48, v48
	v_mul_f32_e32 v71, v49, v49
	v_mul_f32_e32 v72, v50, v50
	v_mul_f32_e32 v73, v51, v51
	v_cvt_pk_bf16_f32 v48, v60, v61
	v_cvt_pk_bf16_f32 v49, v62, v63
	v_cvt_pk_bf16_f32 v50, v56, v57
	v_cvt_pk_bf16_f32 v51, v58, v59
	v_mul_f32_e32 v52, v52, v52
	v_mul_f32_e32 v53, v53, v53
	v_mul_f32_e32 v54, v54, v54
	v_mul_f32_e32 v55, v55, v55
	global_store_dwordx4 v[66:67], v[48:51], off
	s_nop 1
	v_cvt_pk_bf16_f32 v48, v52, v53
	v_cvt_pk_bf16_f32 v49, v54, v55
	v_cvt_pk_bf16_f32 v50, v70, v71
	v_cvt_pk_bf16_f32 v51, v72, v73
	global_store_dwordx4 v[66:67], v[48:51], off offset:256
	s_nop 1
	v_mov_b64_e32 v[48:49], v[222:223]
	v_mov_b64_e32 v[50:51], v[224:225]
	v_mov_b64_e32 v[52:53], v[226:227]
	v_mov_b64_e32 v[54:55], v[228:229]
	v_mov_b32_e32 v56, v48
	v_mov_b32_e32 v57, v52
	v_mov_b32_e32 v52, v49
	v_mov_b32_e32 v48, v50
	v_mov_b32_e32 v49, v54
	v_mov_b32_e32 v54, v51
	v_pk_add_f32 v[50:51], v[56:57], v[52:53]
	v_pk_add_f32 v[48:49], v[48:49], v[54:55]
	s_nop 0
	v_pk_add_f32 v[48:49], v[50:51], v[48:49]
	v_lshlrev_b64 v[50:51], 14, v[64:65]
	v_add_f32_e32 v48, v48, v49
	ds_bpermute_b32 v49, v176, v48
	v_lshl_add_u64 v[50:51], s[16:17], 0, v[50:51]
	v_lshl_add_u64 v[50:51], v[50:51], 0, v[164:165]
	s_waitcnt lgkmcnt(0)
; __device__ __forceinline__ unsigned cvt_pk_bf16(float lo, float hi) { unsigned r; asm volatile("v_cvt_pk_bf16_f32 %0, %1, %2" : "=v"(r) : "v"(lo), "v"(hi)); return r; }
;     __device__ __forceinline__ void operator()(const f32x4 (&acc)[2][2][4][2], const Unit& u, int wr, int wc, int fr, int fq) const {
;     ...
;             for (int m = 0; m < 4; ++m) { const int row = row0 + ai * HALF + m * 16; bf16_t* rowp = O + (size_t)row * FF + col0; float rs;
;                 if constexpr (SUMP) { const f32x4 p0 = *(const f32x4*)(rstd + (size_t)row * 32 + 8 * fq), p1 = *(const f32x4*)(rstd + (size_t)row * 32 + 8 * fq + 4);
;                     float t = ((p0[0] + p0[1]) + (p0[2] + p0[3])) + ((p1[0] + p1[1]) + (p1[2] + p1[3])); t += __shfl_xor(t, 16); t += __shfl_xor(t, 32); rs = rsqrtf(t * (1.f / D) + EPS); }
;                 else rs = rstd[row];
; #pragma unroll
;                 for (int bj = 0; bj < 2; ++bj) { f32x4 v0 = acc[ai][bj][m][0] * rs + bv[bj][0], v1 = acc[ai][bj][m][1] * rs + bv[bj][1];
; #pragma unroll
;                     for (int e = 0; e < 4; ++e) { const float a = fmaxf(v0[e], 0.f), b = fmaxf(v1[e], 0.f); v0[e] = a * a; v1[e] = b * b; }
;                     u32x4 w; w.x = cvt_pk_bf16(v0[0], v0[1]); w.y = cvt_pk_bf16(v0[2], v0[3]); w.z = cvt_pk_bf16(v1[0], v1[1]); w.w = cvt_pk_bf16(v1[2], v1[3]);
;                     *(u32x4*)(rowp + bj * HALF) = w; } }
	v_add_f32_e32 v54, v48, v49
	ds_bpermute_b32 v55, v177, v54
	v_add_u32_e32 v48, 0xa0, v166
	v_ashrrev_i32_e32 v49, 31, v48
	v_lshlrev_b64 v[52:53], 7, v[48:49]
	v_lshl_add_u64 v[52:53], v[154:155], 0, v[52:53]
	s_waitcnt lgkmcnt(0)
	v_add_f32_e32 v54, v54, v55
	v_fmamk_f32 v54, v54, 0x3a000000, v175
	v_mul_f32_e32 v55, 0x4b800000, v54
	v_cmp_gt_f32_e32 vcc, s58, v54
	s_nop 1
	v_cndmask_b32_e32 v54, v54, v55, vcc
	v_rsq_f32_e32 v54, v54
	s_nop 0
	v_mul_f32_e32 v55, 0x45800000, v54
	v_cndmask_b32_e32 v54, v54, v55, vcc
	v_pk_fma_f32 v[46:47], v[46:47], v[54:55], v[94:95] op_sel_hi:[1,0,1]
	v_pk_fma_f32 v[44:45], v[44:45], v[54:55], v[92:93] op_sel_hi:[1,0,1]
	v_pk_fma_f32 v[42:43], v[42:43], v[54:55], v[90:91] op_sel_hi:[1,0,1]
	v_pk_fma_f32 v[40:41], v[40:41], v[54:55], v[88:89] op_sel_hi:[1,0,1]
	v_pk_fma_f32 v[34:35], v[34:35], v[54:55], v[82:83] op_sel_hi:[1,0,1]
	v_pk_fma_f32 v[32:33], v[32:33], v[54:55], v[80:81] op_sel_hi:[1,0,1]
	v_pk_fma_f32 v[38:39], v[38:39], v[54:55], v[86:87] op_sel_hi:[1,0,1]
	v_pk_fma_f32 v[36:37], v[36:37], v[54:55], v[84:85] op_sel_hi:[1,0,1]
	v_max_f32_e32 v44, 0, v44
	v_max_f32_e32 v40, 0, v40
	v_max_f32_e32 v45, 0, v45
	v_max_f32_e32 v41, 0, v41
	v_max_f32_e32 v46, 0, v46
	v_max_f32_e32 v42, 0, v42
	v_max_f32_e32 v47, 0, v47
	v_max_f32_e32 v43, 0, v43
	v_max_f32_e32 v32, 0, v32
	v_max_f32_e32 v33, 0, v33
	v_max_f32_e32 v34, 0, v34
	v_max_f32_e32 v35, 0, v35
	v_max_f32_e32 v36, 0, v36
	v_max_f32_e32 v37, 0, v37
	v_max_f32_e32 v38, 0, v38
	v_max_f32_e32 v39, 0, v39
	v_mul_f32_e32 v44, v44, v44
	v_mul_f32_e32 v40, v40, v40
	v_mul_f32_e32 v45, v45, v45
	v_mul_f32_e32 v41, v41, v41
	v_mul_f32_e32 v46, v46, v46
	v_mul_f32_e32 v42, v42, v42
	v_mul_f32_e32 v47, v47, v47
	v_mul_f32_e32 v43, v43, v43
	v_mul_f32_e32 v54, v32, v32
	v_mul_f32_e32 v55, v33, v33
	v_mul_f32_e32 v56, v34, v34
	v_mul_f32_e32 v57, v35, v35
	v_cvt_pk_bf16_f32 v32, v44, v45
	v_cvt_pk_bf16_f32 v33, v46, v47
	v_cvt_pk_bf16_f32 v34, v40, v41
	v_cvt_pk_bf16_f32 v35, v42, v43
	v_mul_f32_e32 v36, v36, v36
	v_mul_f32_e32 v37, v37, v37
	v_mul_f32_e32 v38, v38, v38
	v_mul_f32_e32 v39, v39, v39
	global_store_dwordx4 v[50:51], v[32:35], off
	s_nop 1
	v_cvt_pk_bf16_f32 v32, v36, v37
	v_cvt_pk_bf16_f32 v33, v38, v39
	v_cvt_pk_bf16_f32 v34, v54, v55
	v_cvt_pk_bf16_f32 v35, v56, v57
	global_store_dwordx4 v[50:51], v[32:35], off offset:256
	s_nop 1
	v_mov_b64_e32 v[32:33], v[230:231]
	v_mov_b64_e32 v[34:35], v[232:233]
	v_mov_b64_e32 v[36:37], v[234:235]
	v_mov_b64_e32 v[38:39], v[236:237]
	v_mov_b32_e32 v40, v32
	v_mov_b32_e32 v41, v36
	v_mov_b32_e32 v36, v33
	v_mov_b32_e32 v32, v34
	v_mov_b32_e32 v33, v38
	v_mov_b32_e32 v38, v35
	v_pk_add_f32 v[34:35], v[40:41], v[36:37]
	v_pk_add_f32 v[32:33], v[32:33], v[38:39]
	s_nop 0
	v_pk_add_f32 v[32:33], v[34:35], v[32:33]
	v_lshlrev_b64 v[34:35], 14, v[48:49]
	v_add_f32_e32 v32, v32, v33
	ds_bpermute_b32 v33, v176, v32
	v_lshl_add_u64 v[34:35], s[16:17], 0, v[34:35]
	v_lshl_add_u64 v[34:35], v[34:35], 0, v[164:165]
	s_waitcnt lgkmcnt(0)
	v_add_f32_e32 v38, v32, v33
	ds_bpermute_b32 v39, v177, v38
	v_add_u32_e32 v32, 0xb0, v166
	v_ashrrev_i32_e32 v33, 31, v32
	v_lshlrev_b64 v[36:37], 7, v[32:33]
	v_lshl_add_u64 v[36:37], v[154:155], 0, v[36:37]
	s_waitcnt lgkmcnt(0)
; __device__ __forceinline__ unsigned cvt_pk_bf16(float lo, float hi) { unsigned r; asm volatile("v_cvt_pk_bf16_f32 %0, %1, %2" : "=v"(r) : "v"(lo), "v"(hi)); return r; }
;     __device__ __forceinline__ void operator()(const f32x4 (&acc)[2][2][4][2], const Unit& u, int wr, int wc, int fr, int fq) const {
;     ...
;             for (int m = 0; m < 4; ++m) { const int row = row0 + ai * HALF + m * 16; bf16_t* rowp = O + (size_t)row * FF + col0; float rs;
;                 if constexpr (SUMP) { const f32x4 p0 = *(const f32x4*)(rstd + (size_t)row * 32 + 8 * fq), p1 = *(const f32x4*)(rstd + (size_t)row * 32 + 8 * fq + 4);
;                     float t = ((p0[0] + p0[1]) + (p0[2] + p0[3])) + ((p1[0] + p1[1]) + (p1[2] + p1[3])); t += __shfl_xor(t, 16); t += __shfl_xor(t, 32); rs = rsqrtf(t * (1.f / D) + EPS); }
;                 else rs = rstd[row];
; #pragma unroll
;                 for (int bj = 0; bj < 2; ++bj) { f32x4 v0 = acc[ai][bj][m][0] * rs + bv[bj][0], v1 = acc[ai][bj][m][1] * rs + bv[bj][1];
; #pragma unroll
;                     for (int e = 0; e < 4; ++e) { const float a = fmaxf(v0[e], 0.f), b = fmaxf(v1[e], 0.f); v0[e] = a * a; v1[e] = b * b; }
;                     u32x4 w; w.x = cvt_pk_bf16(v0[0], v0[1]); w.y = cvt_pk_bf16(v0[2], v0[3]); w.z = cvt_pk_bf16(v1[0], v1[1]); w.w = cvt_pk_bf16(v1[2], v1[3]);
;                     *(u32x4*)(rowp + bj * HALF) = w; } }
	v_add_f32_e32 v38, v38, v39
	v_fmamk_f32 v38, v38, 0x3a000000, v175
	v_mul_f32_e32 v39, 0x4b800000, v38
	v_cmp_gt_f32_e32 vcc, s58, v38
	s_nop 1
	v_cndmask_b32_e32 v38, v38, v39, vcc
	v_rsq_f32_e32 v38, v38
	s_nop 0
	v_mul_f32_e32 v39, 0x45800000, v38
	v_cndmask_b32_e32 v38, v38, v39, vcc
	v_pk_fma_f32 v[30:31], v[30:31], v[38:39], v[94:95] op_sel_hi:[1,0,1]
	v_pk_fma_f32 v[28:29], v[28:29], v[38:39], v[92:93] op_sel_hi:[1,0,1]
	v_pk_fma_f32 v[26:27], v[26:27], v[38:39], v[90:91] op_sel_hi:[1,0,1]
	v_pk_fma_f32 v[24:25], v[24:25], v[38:39], v[88:89] op_sel_hi:[1,0,1]
	v_pk_fma_f32 v[18:19], v[18:19], v[38:39], v[82:83] op_sel_hi:[1,0,1]
	v_pk_fma_f32 v[16:17], v[16:17], v[38:39], v[80:81] op_sel_hi:[1,0,1]
	v_pk_fma_f32 v[22:23], v[22:23], v[38:39], v[86:87] op_sel_hi:[1,0,1]
	v_pk_fma_f32 v[20:21], v[20:21], v[38:39], v[84:85] op_sel_hi:[1,0,1]
	v_max_f32_e32 v28, 0, v28
	v_max_f32_e32 v24, 0, v24
	v_max_f32_e32 v29, 0, v29
	v_max_f32_e32 v25, 0, v25
	v_max_f32_e32 v30, 0, v30
	v_max_f32_e32 v26, 0, v26
	v_max_f32_e32 v31, 0, v31
	v_max_f32_e32 v27, 0, v27
	v_max_f32_e32 v16, 0, v16
	v_max_f32_e32 v17, 0, v17
	v_max_f32_e32 v18, 0, v18
	v_max_f32_e32 v19, 0, v19
	v_max_f32_e32 v20, 0, v20
	v_max_f32_e32 v21, 0, v21
	v_max_f32_e32 v22, 0, v22
	v_max_f32_e32 v23, 0, v23
	v_mul_f32_e32 v28, v28, v28
	v_mul_f32_e32 v24, v24, v24
	v_mul_f32_e32 v29, v29, v29
	v_mul_f32_e32 v25, v25, v25
	v_mul_f32_e32 v30, v30, v30
	v_mul_f32_e32 v26, v26, v26
	v_mul_f32_e32 v31, v31, v31
	v_mul_f32_e32 v27, v27, v27
	v_mul_f32_e32 v38, v16, v16
	v_mul_f32_e32 v39, v17, v17
	v_mul_f32_e32 v40, v18, v18
	v_mul_f32_e32 v41, v19, v19
	v_cvt_pk_bf16_f32 v16, v28, v29
	v_cvt_pk_bf16_f32 v17, v30, v31
	v_cvt_pk_bf16_f32 v18, v24, v25
	v_cvt_pk_bf16_f32 v19, v26, v27
	v_mul_f32_e32 v20, v20, v20
	v_mul_f32_e32 v21, v21, v21
	v_mul_f32_e32 v22, v22, v22
	v_mul_f32_e32 v23, v23, v23
	global_store_dwordx4 v[34:35], v[16:19], off
	s_andn2_b64 vcc, exec, s[0:1]
	s_nop 0
	v_cvt_pk_bf16_f32 v16, v20, v21
	v_cvt_pk_bf16_f32 v17, v22, v23
	v_cvt_pk_bf16_f32 v18, v38, v39
	v_cvt_pk_bf16_f32 v19, v40, v41
	global_store_dwordx4 v[34:35], v[16:19], off offset:256
	s_nop 1
	v_mov_b64_e32 v[16:17], v[238:239]
	v_mov_b64_e32 v[18:19], v[240:241]
	v_mov_b64_e32 v[20:21], v[242:243]
	v_mov_b64_e32 v[22:23], v[244:245]
	v_mov_b32_e32 v24, v16
	v_mov_b32_e32 v25, v20
	v_mov_b32_e32 v20, v17
	v_mov_b32_e32 v16, v18
	v_mov_b32_e32 v17, v22
	v_mov_b32_e32 v22, v19
	v_pk_add_f32 v[18:19], v[24:25], v[20:21]
	v_pk_add_f32 v[16:17], v[16:17], v[22:23]
	s_nop 0
	v_pk_add_f32 v[16:17], v[18:19], v[16:17]
	s_nop 0
	v_add_f32_e32 v16, v16, v17
	ds_bpermute_b32 v17, v176, v16
	s_waitcnt lgkmcnt(0)
	v_add_f32_e32 v16, v16, v17
	ds_bpermute_b32 v17, v177, v16
	s_waitcnt lgkmcnt(0)
	v_add_f32_e32 v16, v16, v17
	v_fmamk_f32 v16, v16, 0x3a000000, v175
	v_mul_f32_e32 v17, 0x4b800000, v16
	v_cmp_gt_f32_e64 s[0:1], s58, v16
	s_nop 1
	v_cndmask_b32_e64 v16, v16, v17, s[0:1]
	v_rsq_f32_e32 v18, v16
	v_lshlrev_b64 v[16:17], 14, v[32:33]
	v_lshl_add_u64 v[16:17], s[16:17], 0, v[16:17]
	v_lshl_add_u64 v[16:17], v[16:17], 0, v[164:165]
	v_mul_f32_e32 v19, 0x45800000, v18
	v_cndmask_b32_e64 v18, v18, v19, s[0:1]
	v_pk_fma_f32 v[14:15], v[14:15], v[18:19], v[94:95] op_sel_hi:[1,0,1]
	v_pk_fma_f32 v[12:13], v[12:13], v[18:19], v[92:93] op_sel_hi:[1,0,1]
	v_pk_fma_f32 v[10:11], v[10:11], v[18:19], v[90:91] op_sel_hi:[1,0,1]
	v_pk_fma_f32 v[8:9], v[8:9], v[18:19], v[88:89] op_sel_hi:[1,0,1]
	v_pk_fma_f32 v[2:3], v[2:3], v[18:19], v[82:83] op_sel_hi:[1,0,1]
	v_pk_fma_f32 v[0:1], v[0:1], v[18:19], v[80:81] op_sel_hi:[1,0,1]
	v_pk_fma_f32 v[6:7], v[6:7], v[18:19], v[86:87] op_sel_hi:[1,0,1]
	v_pk_fma_f32 v[4:5], v[4:5], v[18:19], v[84:85] op_sel_hi:[1,0,1]
	v_max_f32_e32 v12, 0, v12
	v_max_f32_e32 v8, 0, v8
	v_max_f32_e32 v13, 0, v13
	v_max_f32_e32 v9, 0, v9
	v_max_f32_e32 v14, 0, v14
	v_max_f32_e32 v10, 0, v10
	v_max_f32_e32 v15, 0, v15
	v_max_f32_e32 v11, 0, v11
	v_max_f32_e32 v0, 0, v0
	v_max_f32_e32 v1, 0, v1
	v_max_f32_e32 v2, 0, v2
	v_max_f32_e32 v3, 0, v3
	v_max_f32_e32 v4, 0, v4
	v_max_f32_e32 v5, 0, v5
	v_max_f32_e32 v6, 0, v6
	v_max_f32_e32 v7, 0, v7
	v_mul_f32_e32 v12, v12, v12
	v_mul_f32_e32 v8, v8, v8
	v_mul_f32_e32 v13, v13, v13
	v_mul_f32_e32 v9, v9, v9
	v_mul_f32_e32 v14, v14, v14
	v_mul_f32_e32 v10, v10, v10
	v_mul_f32_e32 v15, v15, v15
	v_mul_f32_e32 v11, v11, v11
	v_mul_f32_e32 v18, v0, v0
	v_mul_f32_e32 v19, v1, v1
	v_mul_f32_e32 v20, v2, v2
	v_mul_f32_e32 v21, v3, v3
	v_cvt_pk_bf16_f32 v0, v12, v13
	v_cvt_pk_bf16_f32 v1, v14, v15
	v_cvt_pk_bf16_f32 v2, v8, v9
	v_cvt_pk_bf16_f32 v3, v10, v11
	s_mov_b64 s[0:1], -1
	v_mul_f32_e32 v4, v4, v4
	v_mul_f32_e32 v5, v5, v5
	v_mul_f32_e32 v6, v6, v6
	v_mul_f32_e32 v7, v7, v7
	global_store_dwordx4 v[16:17], v[0:3], off
	s_nop 1
	v_cvt_pk_bf16_f32 v0, v4, v5
	v_cvt_pk_bf16_f32 v1, v6, v7
	v_cvt_pk_bf16_f32 v2, v18, v19
	v_cvt_pk_bf16_f32 v3, v20, v21
	global_store_dwordx4 v[16:17], v[0:3], off offset:256
	s_cbranch_vccnz .LBB0_1134
	s_andn2_b64 vcc, exec, s[6:7]
	s_cbranch_vccnz .LBB0_1133
	s_barrier
	s_branch .LBB0_1133

; __global__ void __launch_bounds__(NTHREADS, 2) fwd_megakernel(Args args) {
	.amdhsa_kernel _Z14fwd_megakernel4Args
		.amdhsa_group_segment_fixed_size 0
		.amdhsa_private_segment_fixed_size 0
		.amdhsa_kernarg_size 416
		.amdhsa_user_sgpr_count 2
		.amdhsa_user_sgpr_dispatch_ptr 0
		.amdhsa_user_sgpr_queue_ptr 0
		.amdhsa_user_sgpr_kernarg_segment_ptr 1
		.amdhsa_user_sgpr_dispatch_id 0
		.amdhsa_user_sgpr_kernarg_preload_length 0
		.amdhsa_user_sgpr_kernarg_preload_offset 0
		.amdhsa_user_sgpr_private_segment_size 0
		.amdhsa_uses_dynamic_stack 0
		.amdhsa_enable_private_segment 0
		.amdhsa_system_sgpr_workgroup_id_x 1
		.amdhsa_system_sgpr_workgroup_id_y 0
		.amdhsa_system_sgpr_workgroup_id_z 0
		.amdhsa_system_sgpr_workgroup_info 0
		.amdhsa_system_vgpr_workitem_id 2
		.amdhsa_next_free_vgpr 256
		.amdhsa_next_free_sgpr 98
		.amdhsa_accum_offset 256
		.amdhsa_reserve_vcc 1
		.amdhsa_float_round_mode_32 0
		.amdhsa_float_round_mode_16_64 0
		.amdhsa_float_denorm_mode_32 3
		.amdhsa_float_denorm_mode_16_64 3
		.amdhsa_dx10_clamp 1
		.amdhsa_ieee_mode 1
		.amdhsa_fp16_overflow 0
		.amdhsa_tg_split 0
		.amdhsa_exception_fp_ieee_invalid_op 0
		.amdhsa_exception_fp_denorm_src 0
		.amdhsa_exception_fp_ieee_div_zero 0
		.amdhsa_exception_fp_ieee_overflow 0
		.amdhsa_exception_fp_ieee_underflow 0
		.amdhsa_exception_fp_ieee_inexact 0
		.amdhsa_exception_int_div_zero 0
	.end_amdhsa_kernel

; __global__ void __launch_bounds__(NTHREADS, 2) fwd_megakernel(Args args) {
amdhsa.kernels:
  - .agpr_count:     0
    .args:
      - .offset:         0
        .size:           160
        .value_kind:     by_value
      - .offset:         160
        .size:           4
        .value_kind:     hidden_block_count_x
      - .offset:         164
        .size:           4
        .value_kind:     hidden_block_count_y
      - .offset:         168
        .size:           4
        .value_kind:     hidden_block_count_z
      - .offset:         172
        .size:           2
        .value_kind:     hidden_group_size_x
      - .offset:         174
        .size:           2
        .value_kind:     hidden_group_size_y
      - .offset:         176
        .size:           2
        .value_kind:     hidden_group_size_z
      - .offset:         178
        .size:           2
        .value_kind:     hidden_remainder_x
      - .offset:         180
        .size:           2
        .value_kind:     hidden_remainder_y
      - .offset:         182
        .size:           2
        .value_kind:     hidden_remainder_z
      - .offset:         200
        .size:           8
        .value_kind:     hidden_global_offset_x
      - .offset:         208
        .size:           8
        .value_kind:     hidden_global_offset_y
      - .offset:         216
        .size:           8
        .value_kind:     hidden_global_offset_z
      - .offset:         224
        .size:           2
        .value_kind:     hidden_grid_dims
      - .offset:         248
        .size:           8
        .value_kind:     hidden_multigrid_sync_arg
      - .offset:         280
        .size:           4
        .value_kind:     hidden_dynamic_lds_size
    .group_segment_fixed_size: 0
    .kernarg_segment_align: 8
    .kernarg_segment_size: 416
    .language:       OpenCL C
    .language_version:
      - 2
      - 0
    .max_flat_workgroup_size: 512
    .name:           _Z14fwd_megakernel4Args
    .private_segment_fixed_size: 0
    .sgpr_count:     104
    .sgpr_spill_count: 19
    .symbol:         _Z14fwd_megakernel4Args.kd
    .uniform_work_group_size: 1
    .uses_dynamic_stack: false
    .vgpr_count:     256
    .vgpr_spill_count: 0
    .wavefront_size: 64
